# GEMM3 output stores write full 128-byte lines: n0/n1 fragments exchanged between lane halves with DPP so each store covers 8 rows x 128 B
# baseline (speedup 1.0000x reference)
;     DI bool operator()(f32x4 (&acc)[2][2][4][2], const pg8::Unit& u, int wr, int wc, int fr, int fq) const {
;     ...
;         const unsigned soff = (unsigned)(((wr * 64 + fr) * 16 + fq * 4) * 8);
;         const char* lgt = (const char*)(ln_g + pn * 256); const char* lbt = (const char*)(ln_b + pn * 256);
; #pragma unroll
;         for (int ai = 0; ai < 2; ++ai)
; #pragma unroll
;             for (int m = 0; m < 4; ++m) {
;                 const char* sr = (const char*)st + (size_t)(ai * 128 + m * 16) * 16 * 8;
;                 float t1 = 0.f, t2 = 0.f;
; #pragma unroll
;                 for (int t = 0; t < 4; ++t) { const unsigned long long w = __hip_atomic_load((const unsigned long long*)(sr + soff + t * 8), __ATOMIC_RELAXED, __HIP_MEMORY_SCOPE_AGENT); t1 += __uint_as_float((unsigned)w); t2 += __uint_as_float((unsigned)(w >> 32)); }
;                 t1 += __shfl_xor(t1, 16); t1 += __shfl_xor(t1, 32); t2 += __shfl_xor(t2, 16); t2 += __shfl_xor(t2, 32);
;                 const float mean = t1 * (1.0f / 4096.0f), var = fmaxf(t2 * (1.0f / 4096.0f) - mean * mean, 0.f), rstd = rsqrtf(var + 1e-6f);
;                 char* orow = ot + (size_t)(ai * 128 + m * 16) * DM * 4;
; #pragma unroll
;                 for (int bj = 0; bj < 2; ++bj)
; #pragma unroll
;                     for (int n = 0; n < 2; ++n) { const f32x4 gg = *(const f32x4*)(lgt + coff + (bj * 128 + n * 16) * 4), bb = *(const f32x4*)(lbt + coff + (bj * 128 + n * 16) * 4);
;                         *(f32x4*)(orow + loff + (bj * 128 + n * 16) * 4) = (acc[ai][bj][m][n] - mean) * rstd * gg + bb; }
.LBB0_909:
	v_lshlrev_b32_e32 v128, 5, v168
	s_waitcnt lgkmcnt(0)
	buffer_inv sc1
	s_waitcnt vmcnt(0)
	v_lshl_or_b32 v134, v169, 7, v128
	v_add_u32_e32 v135, 0x1000, v134
	v_add_u32_e32 v136, 0x4000, v134
	v_add_u32_e32 v137, 0x5000, v134
	global_load_dwordx2 v[172:173], v134, s[28:29] sc1
	global_load_dwordx2 v[174:175], v134, s[28:29] offset:8 sc1
	global_load_dwordx2 v[176:177], v134, s[28:29] offset:16 sc1
	global_load_dwordx2 v[178:179], v134, s[28:29] offset:24 sc1
	global_load_dwordx2 v[180:181], v134, s[28:29] offset:2048 sc1
	global_load_dwordx2 v[182:183], v134, s[28:29] offset:2056 sc1
	global_load_dwordx2 v[184:185], v134, s[28:29] offset:2064 sc1
	global_load_dwordx2 v[186:187], v134, s[28:29] offset:2072 sc1
	global_load_dwordx2 v[188:189], v135, s[28:29] sc1
	global_load_dwordx2 v[190:191], v135, s[28:29] offset:8 sc1
	global_load_dwordx2 v[192:193], v135, s[28:29] offset:16 sc1
	global_load_dwordx2 v[194:195], v135, s[28:29] offset:24 sc1
	global_load_dwordx2 v[198:199], v135, s[28:29] offset:2048 sc1
	global_load_dwordx2 v[200:201], v135, s[28:29] offset:2056 sc1
	global_load_dwordx2 v[202:203], v135, s[28:29] offset:2064 sc1
	global_load_dwordx2 v[204:205], v135, s[28:29] offset:2072 sc1
	global_load_dwordx2 v[206:207], v136, s[28:29] sc1
	global_load_dwordx2 v[208:209], v136, s[28:29] offset:8 sc1
	global_load_dwordx2 v[210:211], v136, s[28:29] offset:16 sc1
	global_load_dwordx2 v[212:213], v136, s[28:29] offset:24 sc1
	global_load_dwordx2 v[214:215], v136, s[28:29] offset:2048 sc1
	global_load_dwordx2 v[216:217], v136, s[28:29] offset:2056 sc1
	global_load_dwordx2 v[218:219], v136, s[28:29] offset:2064 sc1
	global_load_dwordx2 v[220:221], v136, s[28:29] offset:2072 sc1
	global_load_dwordx2 v[222:223], v137, s[28:29] sc1
	global_load_dwordx2 v[138:139], v137, s[28:29] offset:8 sc1
	global_load_dwordx2 v[140:141], v137, s[28:29] offset:16 sc1
	global_load_dwordx2 v[142:143], v137, s[28:29] offset:24 sc1
	global_load_dwordx2 v[156:157], v137, s[28:29] offset:2048 sc1
	global_load_dwordx2 v[158:159], v137, s[28:29] offset:2056 sc1
	global_load_dwordx2 v[168:169], v137, s[28:29] offset:2064 sc1
	global_load_dwordx2 v[170:171], v137, s[28:29] offset:2072 sc1
	s_lshl_b64 s[24:25], s[24:25], 2
	s_add_u32 s24, s72, s24
	s_addc_u32 s25, s73, s25
	s_add_u32 s24, s24, s26
	s_addc_u32 s25, s25, s27
	s_add_u32 s30, s52, s26
	s_addc_u32 s31, s53, s27
	s_add_u32 s26, s54, s26
	s_addc_u32 s27, s55, s27
	v_lshl_add_u64 v[128:129], s[30:31], 0, v[148:149]
	v_lshl_add_u64 v[130:131], s[26:27], 0, v[148:149]
	global_load_dwordx4 v[224:227], v[128:129], off
	global_load_dwordx4 v[228:231], v[128:129], off offset:64
	global_load_dwordx4 v[232:235], v[128:129], off offset:512
	global_load_dwordx4 v[236:239], v[128:129], off offset:576
	global_load_dwordx4 v[240:243], v[130:131], off
	global_load_dwordx4 v[244:247], v[130:131], off offset:64
	global_load_dwordx4 v[248:251], v[130:131], off offset:512
	global_load_dwordx4 v[252:255], v[130:131], off offset:576
	v_lshl_add_u64 v[132:133], s[24:25], 0, v[154:155]
	s_mov_b32 s24, s82
	s_waitcnt vmcnt(8)
	v_pk_add_f32 v[172:173], v[172:173], v[174:175]
	v_pk_add_f32 v[180:181], v[180:181], v[182:183]
	v_pk_add_f32 v[188:189], v[188:189], v[190:191]
	v_pk_add_f32 v[198:199], v[198:199], v[200:201]
	v_pk_add_f32 v[206:207], v[206:207], v[208:209]
	v_pk_add_f32 v[214:215], v[214:215], v[216:217]
	v_pk_add_f32 v[222:223], v[222:223], v[138:139]
	v_pk_add_f32 v[156:157], v[156:157], v[158:159]
	v_pk_add_f32 v[172:173], v[172:173], v[176:177]
	v_pk_add_f32 v[180:181], v[180:181], v[184:185]
	v_pk_add_f32 v[188:189], v[188:189], v[192:193]
	v_pk_add_f32 v[198:199], v[198:199], v[202:203]
	v_pk_add_f32 v[206:207], v[206:207], v[210:211]
	v_pk_add_f32 v[214:215], v[214:215], v[218:219]
	v_pk_add_f32 v[222:223], v[222:223], v[140:141]
	v_pk_add_f32 v[156:157], v[156:157], v[168:169]
	v_pk_add_f32 v[172:173], v[172:173], v[178:179]
	v_pk_add_f32 v[180:181], v[180:181], v[186:187]
	v_pk_add_f32 v[188:189], v[188:189], v[194:195]
	v_pk_add_f32 v[198:199], v[198:199], v[204:205]
	v_pk_add_f32 v[206:207], v[206:207], v[212:213]
	v_pk_add_f32 v[214:215], v[214:215], v[220:221]
	v_pk_add_f32 v[222:223], v[222:223], v[142:143]
	v_pk_add_f32 v[156:157], v[156:157], v[170:171]
	ds_bpermute_b32 v174, v166, v172
	ds_bpermute_b32 v175, v166, v173
	ds_bpermute_b32 v182, v166, v180
	ds_bpermute_b32 v183, v166, v181
	ds_bpermute_b32 v190, v166, v188
	ds_bpermute_b32 v191, v166, v189
	ds_bpermute_b32 v200, v166, v198
	ds_bpermute_b32 v201, v166, v199
	ds_bpermute_b32 v208, v166, v206
	ds_bpermute_b32 v209, v166, v207
	ds_bpermute_b32 v216, v166, v214
	ds_bpermute_b32 v217, v166, v215
	ds_bpermute_b32 v138, v166, v222
	ds_bpermute_b32 v139, v166, v223
	ds_bpermute_b32 v158, v166, v156
	ds_bpermute_b32 v159, v166, v157
	s_waitcnt lgkmcnt(0)
	v_pk_add_f32 v[172:173], v[172:173], v[174:175]
	v_pk_add_f32 v[180:181], v[180:181], v[182:183]
	v_pk_add_f32 v[188:189], v[188:189], v[190:191]
	v_pk_add_f32 v[198:199], v[198:199], v[200:201]
	v_pk_add_f32 v[206:207], v[206:207], v[208:209]
	v_pk_add_f32 v[214:215], v[214:215], v[216:217]
	v_pk_add_f32 v[222:223], v[222:223], v[138:139]
	v_pk_add_f32 v[156:157], v[156:157], v[158:159]
	ds_bpermute_b32 v176, v167, v172
	ds_bpermute_b32 v177, v167, v173
	ds_bpermute_b32 v184, v167, v180
	ds_bpermute_b32 v185, v167, v181
	ds_bpermute_b32 v192, v167, v188
	ds_bpermute_b32 v193, v167, v189
	ds_bpermute_b32 v202, v167, v198
	ds_bpermute_b32 v203, v167, v199
	ds_bpermute_b32 v210, v167, v206
	ds_bpermute_b32 v211, v167, v207
	ds_bpermute_b32 v218, v167, v214
	ds_bpermute_b32 v219, v167, v215
	ds_bpermute_b32 v140, v167, v222
	ds_bpermute_b32 v141, v167, v223
	ds_bpermute_b32 v168, v167, v156
	ds_bpermute_b32 v169, v167, v157
	s_waitcnt lgkmcnt(0)
;     DI bool operator()(f32x4 (&acc)[2][2][4][2], const pg8::Unit& u, int wr, int wc, int fr, int fq) const {
;     ...
;                 const float mean = t1 * (1.0f / 4096.0f), var = fmaxf(t2 * (1.0f / 4096.0f) - mean * mean, 0.f), rstd = rsqrtf(var + 1e-6f);
;                 char* orow = ot + (size_t)(ai * 128 + m * 16) * DM * 4;
; #pragma unroll
;                 for (int bj = 0; bj < 2; ++bj)
; #pragma unroll
;                     for (int n = 0; n < 2; ++n) { const f32x4 gg = *(const f32x4*)(lgt + coff + (bj * 128 + n * 16) * 4), bb = *(const f32x4*)(lbt + coff + (bj * 128 + n * 16) * 4);
;                         *(f32x4*)(orow + loff + (bj * 128 + n * 16) * 4) = (acc[ai][bj][m][n] - mean) * rstd * gg + bb; }
	v_pk_add_f32 v[172:173], v[172:173], v[176:177]
	v_pk_add_f32 v[180:181], v[180:181], v[184:185]
	v_pk_add_f32 v[188:189], v[188:189], v[192:193]
	v_pk_add_f32 v[198:199], v[198:199], v[202:203]
	v_pk_add_f32 v[206:207], v[206:207], v[210:211]
	v_pk_add_f32 v[214:215], v[214:215], v[218:219]
	v_pk_add_f32 v[222:223], v[222:223], v[140:141]
	v_pk_add_f32 v[156:157], v[156:157], v[168:169]
	v_pk_mul_f32 v[172:173], v[172:173], s[22:23] op_sel_hi:[1,0]
	v_pk_mul_f32 v[180:181], v[180:181], s[22:23] op_sel_hi:[1,0]
	v_pk_mul_f32 v[188:189], v[188:189], s[22:23] op_sel_hi:[1,0]
	v_pk_mul_f32 v[198:199], v[198:199], s[22:23] op_sel_hi:[1,0]
	v_pk_mul_f32 v[206:207], v[206:207], s[22:23] op_sel_hi:[1,0]
	v_pk_mul_f32 v[214:215], v[214:215], s[22:23] op_sel_hi:[1,0]
	v_pk_mul_f32 v[222:223], v[222:223], s[22:23] op_sel_hi:[1,0]
	v_pk_mul_f32 v[156:157], v[156:157], s[22:23] op_sel_hi:[1,0]
	v_fma_f32 v174, -v172, v172, v173
	v_fma_f32 v182, -v180, v180, v181
	v_fma_f32 v190, -v188, v188, v189
	v_fma_f32 v200, -v198, v198, v199
	v_fma_f32 v208, -v206, v206, v207
	v_fma_f32 v216, -v214, v214, v215
	v_fma_f32 v138, -v222, v222, v223
	v_fma_f32 v158, -v156, v156, v157
	v_max_f32_e32 v174, 0, v174
	v_max_f32_e32 v182, 0, v182
	v_max_f32_e32 v190, 0, v190
	v_max_f32_e32 v200, 0, v200
	v_max_f32_e32 v208, 0, v208
	v_max_f32_e32 v216, 0, v216
	v_max_f32_e32 v138, 0, v138
	v_max_f32_e32 v158, 0, v158
	v_add_f32_e32 v174, 0x358637bd, v174
	v_add_f32_e32 v182, 0x358637bd, v182
	v_add_f32_e32 v190, 0x358637bd, v190
	v_add_f32_e32 v200, 0x358637bd, v200
	v_add_f32_e32 v208, 0x358637bd, v208
	v_add_f32_e32 v216, 0x358637bd, v216
	v_add_f32_e32 v138, 0x358637bd, v138
	v_add_f32_e32 v158, 0x358637bd, v158
	v_rsq_f32_e32 v174, v174
	v_rsq_f32_e32 v182, v182
	v_rsq_f32_e32 v190, v190
	v_rsq_f32_e32 v200, v200
	v_rsq_f32_e32 v208, v208
	v_rsq_f32_e32 v216, v216
	v_rsq_f32_e32 v138, v138
	v_rsq_f32_e32 v158, v158
	v_add_co_u32_e32 v184, vcc, 0x40000, v132
	s_nop 1
	v_addc_co_u32_e32 v185, vcc, 0, v133, vcc
	v_add_co_u32_e32 v192, vcc, 0x80000, v132
	s_nop 1
	v_addc_co_u32_e32 v193, vcc, 0, v133, vcc
	v_add_co_u32_e32 v202, vcc, 0xc0000, v132
	s_nop 1
	v_addc_co_u32_e32 v203, vcc, 0, v133, vcc
	v_add_co_u32_e32 v210, vcc, 0x200000, v132
	s_nop 1
	v_addc_co_u32_e32 v211, vcc, 0, v133, vcc
	v_add_co_u32_e32 v218, vcc, 0x240000, v132
	s_nop 1
	v_addc_co_u32_e32 v219, vcc, 0, v133, vcc
	v_add_co_u32_e32 v140, vcc, 0x280000, v132
	s_nop 1
	v_addc_co_u32_e32 v141, vcc, 0, v133, vcc
	v_add_co_u32_e32 v168, vcc, 0x2c0000, v132
	s_nop 1
	v_addc_co_u32_e32 v169, vcc, 0, v133, vcc
	s_waitcnt vmcnt(0)
	v_mbcnt_lo_u32_b32 v128, -1, 0
	v_mbcnt_hi_u32_b32 v128, -1, v128
	v_and_b32_e32 v128, 8, v128
	v_mov_b32_e32 v129, 0xfffe0040
	v_cmp_ne_u32_e32 vcc, 0, v128
	s_nop 1
	v_cndmask_b32_e32 v130, 0, v129, vcc
	v_cndmask_b32_e64 v131, 0, -1, vcc
	v_add_co_u32_e32 v132, vcc, v132, v130
	s_nop 1
	v_addc_co_u32_e32 v133, vcc, v133, v131, vcc
	v_add_co_u32_e32 v184, vcc, v184, v130
	s_nop 1
	v_addc_co_u32_e32 v185, vcc, v185, v131, vcc
	v_add_co_u32_e32 v192, vcc, v192, v130
	s_nop 1
	v_addc_co_u32_e32 v193, vcc, v193, v131, vcc
	v_add_co_u32_e32 v202, vcc, v202, v130
	s_nop 1
	v_addc_co_u32_e32 v203, vcc, v203, v131, vcc
	v_add_co_u32_e32 v210, vcc, v210, v130
	s_nop 1
	v_addc_co_u32_e32 v211, vcc, v211, v131, vcc
	v_add_co_u32_e32 v218, vcc, v218, v130
	s_nop 1
	v_addc_co_u32_e32 v219, vcc, v219, v131, vcc
	v_add_co_u32_e32 v140, vcc, v140, v130
	s_nop 1
	v_addc_co_u32_e32 v141, vcc, v141, v131, vcc
	v_add_co_u32_e32 v168, vcc, v168, v130
	s_nop 1
	v_addc_co_u32_e32 v169, vcc, v169, v131, vcc
	v_add_co_u32_e32 v178, vcc, 0x20000, v132
	s_nop 1
	v_addc_co_u32_e32 v179, vcc, 0, v133, vcc
	v_sub_f32_e32 v127, v127, v172
	v_sub_f32_e32 v126, v126, v172
	v_sub_f32_e32 v125, v125, v172
	v_sub_f32_e32 v124, v124, v172
	v_pk_mul_f32 v[124:125], v[124:125], v[174:175] op_sel_hi:[1,0]
	v_pk_mul_f32 v[126:127], v[126:127], v[174:175] op_sel_hi:[1,0]
	v_pk_fma_f32 v[124:125], v[224:225], v[124:125], v[240:241]
	v_pk_fma_f32 v[126:127], v[226:227], v[126:127], v[242:243]
	v_sub_f32_e32 v123, v123, v172
	v_sub_f32_e32 v122, v122, v172
	v_sub_f32_e32 v121, v121, v172
	v_sub_f32_e32 v120, v120, v172
	v_pk_mul_f32 v[120:121], v[120:121], v[174:175] op_sel_hi:[1,0]
	v_pk_mul_f32 v[122:123], v[122:123], v[174:175] op_sel_hi:[1,0]
	v_pk_fma_f32 v[120:121], v[228:229], v[120:121], v[244:245]
	v_pk_fma_f32 v[122:123], v[230:231], v[122:123], v[246:247]
	v_mov_b32_e32 v134, v124
	v_mov_b32_e32 v135, v125
	v_mov_b32_e32 v136, v126
	v_mov_b32_e32 v137, v127
	v_mov_b32_dpp v124, v120 row_ror:8 row_mask:0xf bank_mask:0xc
	v_mov_b32_dpp v125, v121 row_ror:8 row_mask:0xf bank_mask:0xc
	v_mov_b32_dpp v126, v122 row_ror:8 row_mask:0xf bank_mask:0xc
	v_mov_b32_dpp v127, v123 row_ror:8 row_mask:0xf bank_mask:0xc
	v_mov_b32_dpp v120, v134 row_ror:8 row_mask:0xf bank_mask:0x3
	v_mov_b32_dpp v121, v135 row_ror:8 row_mask:0xf bank_mask:0x3
	v_mov_b32_dpp v122, v136 row_ror:8 row_mask:0xf bank_mask:0x3
	v_mov_b32_dpp v123, v137 row_ror:8 row_mask:0xf bank_mask:0x3
	global_store_dwordx4 v[132:133], v[124:127], off
	global_store_dwordx4 v[178:179], v[120:123], off
	v_sub_f32_e32 v119, v119, v172
	v_sub_f32_e32 v118, v118, v172
	v_sub_f32_e32 v117, v117, v172
	v_sub_f32_e32 v116, v116, v172
	v_pk_mul_f32 v[116:117], v[116:117], v[174:175] op_sel_hi:[1,0]
	v_pk_mul_f32 v[118:119], v[118:119], v[174:175] op_sel_hi:[1,0]
	v_pk_fma_f32 v[116:117], v[232:233], v[116:117], v[248:249]
	v_pk_fma_f32 v[118:119], v[234:235], v[118:119], v[250:251]
	v_sub_f32_e32 v115, v115, v172
	v_sub_f32_e32 v114, v114, v172
	v_sub_f32_e32 v113, v113, v172
;     DI bool operator()(f32x4 (&acc)[2][2][4][2], const pg8::Unit& u, int wr, int wc, int fr, int fq) const {
;     ...
;                 char* orow = ot + (size_t)(ai * 128 + m * 16) * DM * 4;
; #pragma unroll
;                 for (int bj = 0; bj < 2; ++bj)
; #pragma unroll
;                     for (int n = 0; n < 2; ++n) { const f32x4 gg = *(const f32x4*)(lgt + coff + (bj * 128 + n * 16) * 4), bb = *(const f32x4*)(lbt + coff + (bj * 128 + n * 16) * 4);
;                         *(f32x4*)(orow + loff + (bj * 128 + n * 16) * 4) = (acc[ai][bj][m][n] - mean) * rstd * gg + bb; }
	v_sub_f32_e32 v112, v112, v172
	v_pk_mul_f32 v[112:113], v[112:113], v[174:175] op_sel_hi:[1,0]
	v_pk_mul_f32 v[114:115], v[114:115], v[174:175] op_sel_hi:[1,0]
	v_pk_fma_f32 v[112:113], v[236:237], v[112:113], v[252:253]
	v_pk_fma_f32 v[114:115], v[238:239], v[114:115], v[254:255]
	v_mov_b32_e32 v134, v116
	v_mov_b32_e32 v135, v117
	v_mov_b32_e32 v136, v118
	v_mov_b32_e32 v137, v119
	v_mov_b32_dpp v116, v112 row_ror:8 row_mask:0xf bank_mask:0xc
	v_mov_b32_dpp v117, v113 row_ror:8 row_mask:0xf bank_mask:0xc
	v_mov_b32_dpp v118, v114 row_ror:8 row_mask:0xf bank_mask:0xc
	v_mov_b32_dpp v119, v115 row_ror:8 row_mask:0xf bank_mask:0xc
	v_mov_b32_dpp v112, v134 row_ror:8 row_mask:0xf bank_mask:0x3
	v_mov_b32_dpp v113, v135 row_ror:8 row_mask:0xf bank_mask:0x3
	v_mov_b32_dpp v114, v136 row_ror:8 row_mask:0xf bank_mask:0x3
	v_mov_b32_dpp v115, v137 row_ror:8 row_mask:0xf bank_mask:0x3
	global_store_dwordx4 v[132:133], v[116:119], off offset:512
	global_store_dwordx4 v[178:179], v[112:115], off offset:512
	v_add_co_u32_e32 v186, vcc, 0x20000, v184
	s_nop 1
	v_addc_co_u32_e32 v187, vcc, 0, v185, vcc
	v_sub_f32_e32 v111, v111, v180
	v_sub_f32_e32 v110, v110, v180
	v_sub_f32_e32 v109, v109, v180
	v_sub_f32_e32 v108, v108, v180
	v_pk_mul_f32 v[108:109], v[108:109], v[182:183] op_sel_hi:[1,0]
	v_pk_mul_f32 v[110:111], v[110:111], v[182:183] op_sel_hi:[1,0]
	v_pk_fma_f32 v[108:109], v[224:225], v[108:109], v[240:241]
	v_pk_fma_f32 v[110:111], v[226:227], v[110:111], v[242:243]
	v_sub_f32_e32 v107, v107, v180
	v_sub_f32_e32 v106, v106, v180
	v_sub_f32_e32 v105, v105, v180
	v_sub_f32_e32 v104, v104, v180
	v_pk_mul_f32 v[104:105], v[104:105], v[182:183] op_sel_hi:[1,0]
	v_pk_mul_f32 v[106:107], v[106:107], v[182:183] op_sel_hi:[1,0]
	v_pk_fma_f32 v[104:105], v[228:229], v[104:105], v[244:245]
	v_pk_fma_f32 v[106:107], v[230:231], v[106:107], v[246:247]
	v_mov_b32_e32 v134, v108
	v_mov_b32_e32 v135, v109
	v_mov_b32_e32 v136, v110
	v_mov_b32_e32 v137, v111
	v_mov_b32_dpp v108, v104 row_ror:8 row_mask:0xf bank_mask:0xc
	v_mov_b32_dpp v109, v105 row_ror:8 row_mask:0xf bank_mask:0xc
	v_mov_b32_dpp v110, v106 row_ror:8 row_mask:0xf bank_mask:0xc
	v_mov_b32_dpp v111, v107 row_ror:8 row_mask:0xf bank_mask:0xc
	v_mov_b32_dpp v104, v134 row_ror:8 row_mask:0xf bank_mask:0x3
	v_mov_b32_dpp v105, v135 row_ror:8 row_mask:0xf bank_mask:0x3
	v_mov_b32_dpp v106, v136 row_ror:8 row_mask:0xf bank_mask:0x3
	v_mov_b32_dpp v107, v137 row_ror:8 row_mask:0xf bank_mask:0x3
	global_store_dwordx4 v[184:185], v[108:111], off
	global_store_dwordx4 v[186:187], v[104:107], off
	v_sub_f32_e32 v103, v103, v180
	v_sub_f32_e32 v102, v102, v180
	v_sub_f32_e32 v101, v101, v180
	v_sub_f32_e32 v100, v100, v180
	v_pk_mul_f32 v[100:101], v[100:101], v[182:183] op_sel_hi:[1,0]
	v_pk_mul_f32 v[102:103], v[102:103], v[182:183] op_sel_hi:[1,0]
	v_pk_fma_f32 v[100:101], v[232:233], v[100:101], v[248:249]
	v_pk_fma_f32 v[102:103], v[234:235], v[102:103], v[250:251]
	v_sub_f32_e32 v99, v99, v180
	v_sub_f32_e32 v98, v98, v180
	v_sub_f32_e32 v97, v97, v180
	v_sub_f32_e32 v96, v96, v180
	v_pk_mul_f32 v[96:97], v[96:97], v[182:183] op_sel_hi:[1,0]
	v_pk_mul_f32 v[98:99], v[98:99], v[182:183] op_sel_hi:[1,0]
	v_pk_fma_f32 v[96:97], v[236:237], v[96:97], v[252:253]
	v_pk_fma_f32 v[98:99], v[238:239], v[98:99], v[254:255]
	v_mov_b32_e32 v134, v100
	v_mov_b32_e32 v135, v101
	v_mov_b32_e32 v136, v102
	v_mov_b32_e32 v137, v103
	v_mov_b32_dpp v100, v96 row_ror:8 row_mask:0xf bank_mask:0xc
	v_mov_b32_dpp v101, v97 row_ror:8 row_mask:0xf bank_mask:0xc
	v_mov_b32_dpp v102, v98 row_ror:8 row_mask:0xf bank_mask:0xc
	v_mov_b32_dpp v103, v99 row_ror:8 row_mask:0xf bank_mask:0xc
	v_mov_b32_dpp v96, v134 row_ror:8 row_mask:0xf bank_mask:0x3
	v_mov_b32_dpp v97, v135 row_ror:8 row_mask:0xf bank_mask:0x3
	v_mov_b32_dpp v98, v136 row_ror:8 row_mask:0xf bank_mask:0x3
	v_mov_b32_dpp v99, v137 row_ror:8 row_mask:0xf bank_mask:0x3
	global_store_dwordx4 v[184:185], v[100:103], off offset:512
	global_store_dwordx4 v[186:187], v[96:99], off offset:512
	v_add_co_u32_e32 v194, vcc, 0x20000, v192
	s_nop 1
	v_addc_co_u32_e32 v195, vcc, 0, v193, vcc
	v_sub_f32_e32 v95, v95, v188
	v_sub_f32_e32 v94, v94, v188
	v_sub_f32_e32 v93, v93, v188
	v_sub_f32_e32 v92, v92, v188
	v_pk_mul_f32 v[92:93], v[92:93], v[190:191] op_sel_hi:[1,0]
	v_pk_mul_f32 v[94:95], v[94:95], v[190:191] op_sel_hi:[1,0]
	v_pk_fma_f32 v[92:93], v[224:225], v[92:93], v[240:241]
	v_pk_fma_f32 v[94:95], v[226:227], v[94:95], v[242:243]
	v_sub_f32_e32 v91, v91, v188
	v_sub_f32_e32 v90, v90, v188
	v_sub_f32_e32 v89, v89, v188
	v_sub_f32_e32 v88, v88, v188
	v_pk_mul_f32 v[88:89], v[88:89], v[190:191] op_sel_hi:[1,0]
	v_pk_mul_f32 v[90:91], v[90:91], v[190:191] op_sel_hi:[1,0]
	v_pk_fma_f32 v[88:89], v[228:229], v[88:89], v[244:245]
	v_pk_fma_f32 v[90:91], v[230:231], v[90:91], v[246:247]
	v_mov_b32_e32 v134, v92
	v_mov_b32_e32 v135, v93
	v_mov_b32_e32 v136, v94
	v_mov_b32_e32 v137, v95
	v_mov_b32_dpp v92, v88 row_ror:8 row_mask:0xf bank_mask:0xc
	v_mov_b32_dpp v93, v89 row_ror:8 row_mask:0xf bank_mask:0xc
	v_mov_b32_dpp v94, v90 row_ror:8 row_mask:0xf bank_mask:0xc
	v_mov_b32_dpp v95, v91 row_ror:8 row_mask:0xf bank_mask:0xc
	v_mov_b32_dpp v88, v134 row_ror:8 row_mask:0xf bank_mask:0x3
	v_mov_b32_dpp v89, v135 row_ror:8 row_mask:0xf bank_mask:0x3
	v_mov_b32_dpp v90, v136 row_ror:8 row_mask:0xf bank_mask:0x3
	v_mov_b32_dpp v91, v137 row_ror:8 row_mask:0xf bank_mask:0x3
	global_store_dwordx4 v[192:193], v[92:95], off
	global_store_dwordx4 v[194:195], v[88:91], off
	v_sub_f32_e32 v87, v87, v188
	v_sub_f32_e32 v86, v86, v188
	v_sub_f32_e32 v85, v85, v188
	v_sub_f32_e32 v84, v84, v188
;     DI bool operator()(f32x4 (&acc)[2][2][4][2], const pg8::Unit& u, int wr, int wc, int fr, int fq) const {
;     ...
;                 char* orow = ot + (size_t)(ai * 128 + m * 16) * DM * 4;
; #pragma unroll
;                 for (int bj = 0; bj < 2; ++bj)
; #pragma unroll
;                     for (int n = 0; n < 2; ++n) { const f32x4 gg = *(const f32x4*)(lgt + coff + (bj * 128 + n * 16) * 4), bb = *(const f32x4*)(lbt + coff + (bj * 128 + n * 16) * 4);
;                         *(f32x4*)(orow + loff + (bj * 128 + n * 16) * 4) = (acc[ai][bj][m][n] - mean) * rstd * gg + bb; }
	v_pk_mul_f32 v[84:85], v[84:85], v[190:191] op_sel_hi:[1,0]
	v_pk_mul_f32 v[86:87], v[86:87], v[190:191] op_sel_hi:[1,0]
	v_pk_fma_f32 v[84:85], v[232:233], v[84:85], v[248:249]
	v_pk_fma_f32 v[86:87], v[234:235], v[86:87], v[250:251]
	v_sub_f32_e32 v83, v83, v188
	v_sub_f32_e32 v82, v82, v188
	v_sub_f32_e32 v81, v81, v188
	v_sub_f32_e32 v80, v80, v188
	v_pk_mul_f32 v[80:81], v[80:81], v[190:191] op_sel_hi:[1,0]
	v_pk_mul_f32 v[82:83], v[82:83], v[190:191] op_sel_hi:[1,0]
	v_pk_fma_f32 v[80:81], v[236:237], v[80:81], v[252:253]
	v_pk_fma_f32 v[82:83], v[238:239], v[82:83], v[254:255]
	v_mov_b32_e32 v134, v84
	v_mov_b32_e32 v135, v85
	v_mov_b32_e32 v136, v86
	v_mov_b32_e32 v137, v87
	v_mov_b32_dpp v84, v80 row_ror:8 row_mask:0xf bank_mask:0xc
	v_mov_b32_dpp v85, v81 row_ror:8 row_mask:0xf bank_mask:0xc
	v_mov_b32_dpp v86, v82 row_ror:8 row_mask:0xf bank_mask:0xc
	v_mov_b32_dpp v87, v83 row_ror:8 row_mask:0xf bank_mask:0xc
	v_mov_b32_dpp v80, v134 row_ror:8 row_mask:0xf bank_mask:0x3
	v_mov_b32_dpp v81, v135 row_ror:8 row_mask:0xf bank_mask:0x3
	v_mov_b32_dpp v82, v136 row_ror:8 row_mask:0xf bank_mask:0x3
	v_mov_b32_dpp v83, v137 row_ror:8 row_mask:0xf bank_mask:0x3
	global_store_dwordx4 v[192:193], v[84:87], off offset:512
	global_store_dwordx4 v[194:195], v[80:83], off offset:512
	v_add_co_u32_e32 v204, vcc, 0x20000, v202
	s_nop 1
	v_addc_co_u32_e32 v205, vcc, 0, v203, vcc
	v_sub_f32_e32 v79, v79, v198
	v_sub_f32_e32 v78, v78, v198
	v_sub_f32_e32 v77, v77, v198
	v_sub_f32_e32 v76, v76, v198
	v_pk_mul_f32 v[76:77], v[76:77], v[200:201] op_sel_hi:[1,0]
	v_pk_mul_f32 v[78:79], v[78:79], v[200:201] op_sel_hi:[1,0]
	v_pk_fma_f32 v[76:77], v[224:225], v[76:77], v[240:241]
	v_pk_fma_f32 v[78:79], v[226:227], v[78:79], v[242:243]
	v_sub_f32_e32 v75, v75, v198
	v_sub_f32_e32 v74, v74, v198
	v_sub_f32_e32 v73, v73, v198
	v_sub_f32_e32 v72, v72, v198
	v_pk_mul_f32 v[72:73], v[72:73], v[200:201] op_sel_hi:[1,0]
	v_pk_mul_f32 v[74:75], v[74:75], v[200:201] op_sel_hi:[1,0]
	v_pk_fma_f32 v[72:73], v[228:229], v[72:73], v[244:245]
	v_pk_fma_f32 v[74:75], v[230:231], v[74:75], v[246:247]
	v_mov_b32_e32 v134, v76
	v_mov_b32_e32 v135, v77
	v_mov_b32_e32 v136, v78
	v_mov_b32_e32 v137, v79
	v_mov_b32_dpp v76, v72 row_ror:8 row_mask:0xf bank_mask:0xc
	v_mov_b32_dpp v77, v73 row_ror:8 row_mask:0xf bank_mask:0xc
	v_mov_b32_dpp v78, v74 row_ror:8 row_mask:0xf bank_mask:0xc
	v_mov_b32_dpp v79, v75 row_ror:8 row_mask:0xf bank_mask:0xc
	v_mov_b32_dpp v72, v134 row_ror:8 row_mask:0xf bank_mask:0x3
	v_mov_b32_dpp v73, v135 row_ror:8 row_mask:0xf bank_mask:0x3
	v_mov_b32_dpp v74, v136 row_ror:8 row_mask:0xf bank_mask:0x3
	v_mov_b32_dpp v75, v137 row_ror:8 row_mask:0xf bank_mask:0x3
	global_store_dwordx4 v[202:203], v[76:79], off
	global_store_dwordx4 v[204:205], v[72:75], off
	v_sub_f32_e32 v71, v71, v198
	v_sub_f32_e32 v70, v70, v198
	v_sub_f32_e32 v69, v69, v198
	v_sub_f32_e32 v68, v68, v198
	v_pk_mul_f32 v[68:69], v[68:69], v[200:201] op_sel_hi:[1,0]
	v_pk_mul_f32 v[70:71], v[70:71], v[200:201] op_sel_hi:[1,0]
	v_pk_fma_f32 v[68:69], v[232:233], v[68:69], v[248:249]
	v_pk_fma_f32 v[70:71], v[234:235], v[70:71], v[250:251]
	v_sub_f32_e32 v67, v67, v198
	v_sub_f32_e32 v66, v66, v198
	v_sub_f32_e32 v65, v65, v198
	v_sub_f32_e32 v64, v64, v198
	v_pk_mul_f32 v[64:65], v[64:65], v[200:201] op_sel_hi:[1,0]
	v_pk_mul_f32 v[66:67], v[66:67], v[200:201] op_sel_hi:[1,0]
	v_pk_fma_f32 v[64:65], v[236:237], v[64:65], v[252:253]
	v_pk_fma_f32 v[66:67], v[238:239], v[66:67], v[254:255]
	v_mov_b32_e32 v134, v68
	v_mov_b32_e32 v135, v69
	v_mov_b32_e32 v136, v70
	v_mov_b32_e32 v137, v71
	v_mov_b32_dpp v68, v64 row_ror:8 row_mask:0xf bank_mask:0xc
	v_mov_b32_dpp v69, v65 row_ror:8 row_mask:0xf bank_mask:0xc
	v_mov_b32_dpp v70, v66 row_ror:8 row_mask:0xf bank_mask:0xc
	v_mov_b32_dpp v71, v67 row_ror:8 row_mask:0xf bank_mask:0xc
	v_mov_b32_dpp v64, v134 row_ror:8 row_mask:0xf bank_mask:0x3
	v_mov_b32_dpp v65, v135 row_ror:8 row_mask:0xf bank_mask:0x3
	v_mov_b32_dpp v66, v136 row_ror:8 row_mask:0xf bank_mask:0x3
	v_mov_b32_dpp v67, v137 row_ror:8 row_mask:0xf bank_mask:0x3
	global_store_dwordx4 v[202:203], v[68:71], off offset:512
	global_store_dwordx4 v[204:205], v[64:67], off offset:512
	v_add_co_u32_e32 v212, vcc, 0x20000, v210
	s_nop 1
	v_addc_co_u32_e32 v213, vcc, 0, v211, vcc
	v_sub_f32_e32 v63, v63, v206
	v_sub_f32_e32 v62, v62, v206
	v_sub_f32_e32 v61, v61, v206
	v_sub_f32_e32 v60, v60, v206
	v_pk_mul_f32 v[60:61], v[60:61], v[208:209] op_sel_hi:[1,0]
	v_pk_mul_f32 v[62:63], v[62:63], v[208:209] op_sel_hi:[1,0]
	v_pk_fma_f32 v[60:61], v[224:225], v[60:61], v[240:241]
	v_pk_fma_f32 v[62:63], v[226:227], v[62:63], v[242:243]
	v_sub_f32_e32 v59, v59, v206
	v_sub_f32_e32 v58, v58, v206
	v_sub_f32_e32 v57, v57, v206
	v_sub_f32_e32 v56, v56, v206
	v_pk_mul_f32 v[56:57], v[56:57], v[208:209] op_sel_hi:[1,0]
	v_pk_mul_f32 v[58:59], v[58:59], v[208:209] op_sel_hi:[1,0]
	v_pk_fma_f32 v[56:57], v[228:229], v[56:57], v[244:245]
	v_pk_fma_f32 v[58:59], v[230:231], v[58:59], v[246:247]
	v_mov_b32_e32 v134, v60
	v_mov_b32_e32 v135, v61
	v_mov_b32_e32 v136, v62
	v_mov_b32_e32 v137, v63
	v_mov_b32_dpp v60, v56 row_ror:8 row_mask:0xf bank_mask:0xc
	v_mov_b32_dpp v61, v57 row_ror:8 row_mask:0xf bank_mask:0xc
	v_mov_b32_dpp v62, v58 row_ror:8 row_mask:0xf bank_mask:0xc
	v_mov_b32_dpp v63, v59 row_ror:8 row_mask:0xf bank_mask:0xc
	v_mov_b32_dpp v56, v134 row_ror:8 row_mask:0xf bank_mask:0x3
	v_mov_b32_dpp v57, v135 row_ror:8 row_mask:0xf bank_mask:0x3
	v_mov_b32_dpp v58, v136 row_ror:8 row_mask:0xf bank_mask:0x3
	v_mov_b32_dpp v59, v137 row_ror:8 row_mask:0xf bank_mask:0x3
;     DI bool operator()(f32x4 (&acc)[2][2][4][2], const pg8::Unit& u, int wr, int wc, int fr, int fq) const {
;     ...
;                 char* orow = ot + (size_t)(ai * 128 + m * 16) * DM * 4;
; #pragma unroll
;                 for (int bj = 0; bj < 2; ++bj)
; #pragma unroll
;                     for (int n = 0; n < 2; ++n) { const f32x4 gg = *(const f32x4*)(lgt + coff + (bj * 128 + n * 16) * 4), bb = *(const f32x4*)(lbt + coff + (bj * 128 + n * 16) * 4);
;                         *(f32x4*)(orow + loff + (bj * 128 + n * 16) * 4) = (acc[ai][bj][m][n] - mean) * rstd * gg + bb; }
	global_store_dwordx4 v[210:211], v[60:63], off
	global_store_dwordx4 v[212:213], v[56:59], off
	v_sub_f32_e32 v55, v55, v206
	v_sub_f32_e32 v54, v54, v206
	v_sub_f32_e32 v53, v53, v206
	v_sub_f32_e32 v52, v52, v206
	v_pk_mul_f32 v[52:53], v[52:53], v[208:209] op_sel_hi:[1,0]
	v_pk_mul_f32 v[54:55], v[54:55], v[208:209] op_sel_hi:[1,0]
	v_pk_fma_f32 v[52:53], v[232:233], v[52:53], v[248:249]
	v_pk_fma_f32 v[54:55], v[234:235], v[54:55], v[250:251]
	v_sub_f32_e32 v51, v51, v206
	v_sub_f32_e32 v50, v50, v206
	v_sub_f32_e32 v49, v49, v206
	v_sub_f32_e32 v48, v48, v206
	v_pk_mul_f32 v[48:49], v[48:49], v[208:209] op_sel_hi:[1,0]
	v_pk_mul_f32 v[50:51], v[50:51], v[208:209] op_sel_hi:[1,0]
	v_pk_fma_f32 v[48:49], v[236:237], v[48:49], v[252:253]
	v_pk_fma_f32 v[50:51], v[238:239], v[50:51], v[254:255]
	v_mov_b32_e32 v134, v52
	v_mov_b32_e32 v135, v53
	v_mov_b32_e32 v136, v54
	v_mov_b32_e32 v137, v55
	v_mov_b32_dpp v52, v48 row_ror:8 row_mask:0xf bank_mask:0xc
	v_mov_b32_dpp v53, v49 row_ror:8 row_mask:0xf bank_mask:0xc
	v_mov_b32_dpp v54, v50 row_ror:8 row_mask:0xf bank_mask:0xc
	v_mov_b32_dpp v55, v51 row_ror:8 row_mask:0xf bank_mask:0xc
	v_mov_b32_dpp v48, v134 row_ror:8 row_mask:0xf bank_mask:0x3
	v_mov_b32_dpp v49, v135 row_ror:8 row_mask:0xf bank_mask:0x3
	v_mov_b32_dpp v50, v136 row_ror:8 row_mask:0xf bank_mask:0x3
	v_mov_b32_dpp v51, v137 row_ror:8 row_mask:0xf bank_mask:0x3
	global_store_dwordx4 v[210:211], v[52:55], off offset:512
	global_store_dwordx4 v[212:213], v[48:51], off offset:512
	v_add_co_u32_e32 v220, vcc, 0x20000, v218
	s_nop 1
	v_addc_co_u32_e32 v221, vcc, 0, v219, vcc
	v_sub_f32_e32 v47, v47, v214
	v_sub_f32_e32 v46, v46, v214
	v_sub_f32_e32 v45, v45, v214
	v_sub_f32_e32 v44, v44, v214
	v_pk_mul_f32 v[44:45], v[44:45], v[216:217] op_sel_hi:[1,0]
	v_pk_mul_f32 v[46:47], v[46:47], v[216:217] op_sel_hi:[1,0]
	v_pk_fma_f32 v[44:45], v[224:225], v[44:45], v[240:241]
	v_pk_fma_f32 v[46:47], v[226:227], v[46:47], v[242:243]
	v_sub_f32_e32 v43, v43, v214
	v_sub_f32_e32 v42, v42, v214
	v_sub_f32_e32 v41, v41, v214
	v_sub_f32_e32 v40, v40, v214
	v_pk_mul_f32 v[40:41], v[40:41], v[216:217] op_sel_hi:[1,0]
	v_pk_mul_f32 v[42:43], v[42:43], v[216:217] op_sel_hi:[1,0]
	v_pk_fma_f32 v[40:41], v[228:229], v[40:41], v[244:245]
	v_pk_fma_f32 v[42:43], v[230:231], v[42:43], v[246:247]
	v_mov_b32_e32 v134, v44
	v_mov_b32_e32 v135, v45
	v_mov_b32_e32 v136, v46
	v_mov_b32_e32 v137, v47
	v_mov_b32_dpp v44, v40 row_ror:8 row_mask:0xf bank_mask:0xc
	v_mov_b32_dpp v45, v41 row_ror:8 row_mask:0xf bank_mask:0xc
	v_mov_b32_dpp v46, v42 row_ror:8 row_mask:0xf bank_mask:0xc
	v_mov_b32_dpp v47, v43 row_ror:8 row_mask:0xf bank_mask:0xc
	v_mov_b32_dpp v40, v134 row_ror:8 row_mask:0xf bank_mask:0x3
	v_mov_b32_dpp v41, v135 row_ror:8 row_mask:0xf bank_mask:0x3
	v_mov_b32_dpp v42, v136 row_ror:8 row_mask:0xf bank_mask:0x3
	v_mov_b32_dpp v43, v137 row_ror:8 row_mask:0xf bank_mask:0x3
	global_store_dwordx4 v[218:219], v[44:47], off
	global_store_dwordx4 v[220:221], v[40:43], off
	v_sub_f32_e32 v39, v39, v214
	v_sub_f32_e32 v38, v38, v214
	v_sub_f32_e32 v37, v37, v214
	v_sub_f32_e32 v36, v36, v214
	v_pk_mul_f32 v[36:37], v[36:37], v[216:217] op_sel_hi:[1,0]
	v_pk_mul_f32 v[38:39], v[38:39], v[216:217] op_sel_hi:[1,0]
	v_pk_fma_f32 v[36:37], v[232:233], v[36:37], v[248:249]
	v_pk_fma_f32 v[38:39], v[234:235], v[38:39], v[250:251]
	v_sub_f32_e32 v35, v35, v214
	v_sub_f32_e32 v34, v34, v214
	v_sub_f32_e32 v33, v33, v214
	v_sub_f32_e32 v32, v32, v214
	v_pk_mul_f32 v[32:33], v[32:33], v[216:217] op_sel_hi:[1,0]
	v_pk_mul_f32 v[34:35], v[34:35], v[216:217] op_sel_hi:[1,0]
	v_pk_fma_f32 v[32:33], v[236:237], v[32:33], v[252:253]
	v_pk_fma_f32 v[34:35], v[238:239], v[34:35], v[254:255]
	v_mov_b32_e32 v134, v36
	v_mov_b32_e32 v135, v37
	v_mov_b32_e32 v136, v38
	v_mov_b32_e32 v137, v39
	v_mov_b32_dpp v36, v32 row_ror:8 row_mask:0xf bank_mask:0xc
	v_mov_b32_dpp v37, v33 row_ror:8 row_mask:0xf bank_mask:0xc
	v_mov_b32_dpp v38, v34 row_ror:8 row_mask:0xf bank_mask:0xc
	v_mov_b32_dpp v39, v35 row_ror:8 row_mask:0xf bank_mask:0xc
	v_mov_b32_dpp v32, v134 row_ror:8 row_mask:0xf bank_mask:0x3
	v_mov_b32_dpp v33, v135 row_ror:8 row_mask:0xf bank_mask:0x3
	v_mov_b32_dpp v34, v136 row_ror:8 row_mask:0xf bank_mask:0x3
	v_mov_b32_dpp v35, v137 row_ror:8 row_mask:0xf bank_mask:0x3
	global_store_dwordx4 v[218:219], v[36:39], off offset:512
	global_store_dwordx4 v[220:221], v[32:35], off offset:512
	v_add_co_u32_e32 v142, vcc, 0x20000, v140
	s_nop 1
	v_addc_co_u32_e32 v143, vcc, 0, v141, vcc
	v_sub_f32_e32 v31, v31, v222
	v_sub_f32_e32 v30, v30, v222
	v_sub_f32_e32 v29, v29, v222
	v_sub_f32_e32 v28, v28, v222
	v_pk_mul_f32 v[28:29], v[28:29], v[138:139] op_sel_hi:[1,0]
	v_pk_mul_f32 v[30:31], v[30:31], v[138:139] op_sel_hi:[1,0]
	v_pk_fma_f32 v[28:29], v[224:225], v[28:29], v[240:241]
	v_pk_fma_f32 v[30:31], v[226:227], v[30:31], v[242:243]
	v_sub_f32_e32 v23, v23, v222
	v_sub_f32_e32 v22, v22, v222
	v_sub_f32_e32 v21, v21, v222
	v_sub_f32_e32 v20, v20, v222
	v_pk_mul_f32 v[20:21], v[20:21], v[138:139] op_sel_hi:[1,0]
	v_pk_mul_f32 v[22:23], v[22:23], v[138:139] op_sel_hi:[1,0]
;     DI bool operator()(f32x4 (&acc)[2][2][4][2], const pg8::Unit& u, int wr, int wc, int fr, int fq) const {
;     ...
;                 char* orow = ot + (size_t)(ai * 128 + m * 16) * DM * 4;
; #pragma unroll
;                 for (int bj = 0; bj < 2; ++bj)
; #pragma unroll
;                     for (int n = 0; n < 2; ++n) { const f32x4 gg = *(const f32x4*)(lgt + coff + (bj * 128 + n * 16) * 4), bb = *(const f32x4*)(lbt + coff + (bj * 128 + n * 16) * 4);
;                         *(f32x4*)(orow + loff + (bj * 128 + n * 16) * 4) = (acc[ai][bj][m][n] - mean) * rstd * gg + bb; }
	v_pk_fma_f32 v[20:21], v[228:229], v[20:21], v[244:245]
	v_pk_fma_f32 v[22:23], v[230:231], v[22:23], v[246:247]
	v_mov_b32_e32 v134, v28
	v_mov_b32_e32 v135, v29
	v_mov_b32_e32 v136, v30
	v_mov_b32_e32 v137, v31
	v_mov_b32_dpp v28, v20 row_ror:8 row_mask:0xf bank_mask:0xc
	v_mov_b32_dpp v29, v21 row_ror:8 row_mask:0xf bank_mask:0xc
	v_mov_b32_dpp v30, v22 row_ror:8 row_mask:0xf bank_mask:0xc
	v_mov_b32_dpp v31, v23 row_ror:8 row_mask:0xf bank_mask:0xc
	v_mov_b32_dpp v20, v134 row_ror:8 row_mask:0xf bank_mask:0x3
	v_mov_b32_dpp v21, v135 row_ror:8 row_mask:0xf bank_mask:0x3
	v_mov_b32_dpp v22, v136 row_ror:8 row_mask:0xf bank_mask:0x3
	v_mov_b32_dpp v23, v137 row_ror:8 row_mask:0xf bank_mask:0x3
	global_store_dwordx4 v[140:141], v[28:31], off
	global_store_dwordx4 v[142:143], v[20:23], off
	v_sub_f32_e32 v15, v15, v222
	v_sub_f32_e32 v14, v14, v222
	v_sub_f32_e32 v13, v13, v222
	v_sub_f32_e32 v12, v12, v222
	v_pk_mul_f32 v[12:13], v[12:13], v[138:139] op_sel_hi:[1,0]
	v_pk_mul_f32 v[14:15], v[14:15], v[138:139] op_sel_hi:[1,0]
	v_pk_fma_f32 v[12:13], v[232:233], v[12:13], v[248:249]
	v_pk_fma_f32 v[14:15], v[234:235], v[14:15], v[250:251]
	v_sub_f32_e32 v7, v7, v222
	v_sub_f32_e32 v6, v6, v222
	v_sub_f32_e32 v5, v5, v222
	v_sub_f32_e32 v4, v4, v222
	v_pk_mul_f32 v[4:5], v[4:5], v[138:139] op_sel_hi:[1,0]
	v_pk_mul_f32 v[6:7], v[6:7], v[138:139] op_sel_hi:[1,0]
	v_pk_fma_f32 v[4:5], v[236:237], v[4:5], v[252:253]
	v_pk_fma_f32 v[6:7], v[238:239], v[6:7], v[254:255]
	v_mov_b32_e32 v134, v12
	v_mov_b32_e32 v135, v13
	v_mov_b32_e32 v136, v14
	v_mov_b32_e32 v137, v15
	v_mov_b32_dpp v12, v4 row_ror:8 row_mask:0xf bank_mask:0xc
	v_mov_b32_dpp v13, v5 row_ror:8 row_mask:0xf bank_mask:0xc
	v_mov_b32_dpp v14, v6 row_ror:8 row_mask:0xf bank_mask:0xc
	v_mov_b32_dpp v15, v7 row_ror:8 row_mask:0xf bank_mask:0xc
	v_mov_b32_dpp v4, v134 row_ror:8 row_mask:0xf bank_mask:0x3
	v_mov_b32_dpp v5, v135 row_ror:8 row_mask:0xf bank_mask:0x3
	v_mov_b32_dpp v6, v136 row_ror:8 row_mask:0xf bank_mask:0x3
	v_mov_b32_dpp v7, v137 row_ror:8 row_mask:0xf bank_mask:0x3
	global_store_dwordx4 v[140:141], v[12:15], off offset:512
	global_store_dwordx4 v[142:143], v[4:7], off offset:512
	v_add_co_u32_e32 v170, vcc, 0x20000, v168
	s_nop 1
	v_addc_co_u32_e32 v171, vcc, 0, v169, vcc
	v_sub_f32_e32 v27, v27, v156
	v_sub_f32_e32 v26, v26, v156
	v_sub_f32_e32 v25, v25, v156
	v_sub_f32_e32 v24, v24, v156
	v_pk_mul_f32 v[24:25], v[24:25], v[158:159] op_sel_hi:[1,0]
	v_pk_mul_f32 v[26:27], v[26:27], v[158:159] op_sel_hi:[1,0]
	v_pk_fma_f32 v[24:25], v[224:225], v[24:25], v[240:241]
	v_pk_fma_f32 v[26:27], v[226:227], v[26:27], v[242:243]
	v_sub_f32_e32 v19, v19, v156
	v_sub_f32_e32 v18, v18, v156
	v_sub_f32_e32 v17, v17, v156
	v_sub_f32_e32 v16, v16, v156
	v_pk_mul_f32 v[16:17], v[16:17], v[158:159] op_sel_hi:[1,0]
	v_pk_mul_f32 v[18:19], v[18:19], v[158:159] op_sel_hi:[1,0]
	v_pk_fma_f32 v[16:17], v[228:229], v[16:17], v[244:245]
	v_pk_fma_f32 v[18:19], v[230:231], v[18:19], v[246:247]
	v_mov_b32_e32 v134, v24
	v_mov_b32_e32 v135, v25
	v_mov_b32_e32 v136, v26
	v_mov_b32_e32 v137, v27
	v_mov_b32_dpp v24, v16 row_ror:8 row_mask:0xf bank_mask:0xc
	v_mov_b32_dpp v25, v17 row_ror:8 row_mask:0xf bank_mask:0xc
	v_mov_b32_dpp v26, v18 row_ror:8 row_mask:0xf bank_mask:0xc
	v_mov_b32_dpp v27, v19 row_ror:8 row_mask:0xf bank_mask:0xc
	v_mov_b32_dpp v16, v134 row_ror:8 row_mask:0xf bank_mask:0x3
	v_mov_b32_dpp v17, v135 row_ror:8 row_mask:0xf bank_mask:0x3
	v_mov_b32_dpp v18, v136 row_ror:8 row_mask:0xf bank_mask:0x3
	v_mov_b32_dpp v19, v137 row_ror:8 row_mask:0xf bank_mask:0x3
	global_store_dwordx4 v[168:169], v[24:27], off
	global_store_dwordx4 v[170:171], v[16:19], off
	v_sub_f32_e32 v11, v11, v156
	v_sub_f32_e32 v10, v10, v156
	v_sub_f32_e32 v9, v9, v156
	v_sub_f32_e32 v8, v8, v156
	v_pk_mul_f32 v[8:9], v[8:9], v[158:159] op_sel_hi:[1,0]
	v_pk_mul_f32 v[10:11], v[10:11], v[158:159] op_sel_hi:[1,0]
	v_pk_fma_f32 v[8:9], v[232:233], v[8:9], v[248:249]
	v_pk_fma_f32 v[10:11], v[234:235], v[10:11], v[250:251]
	v_sub_f32_e32 v3, v3, v156
	v_sub_f32_e32 v2, v2, v156
	v_sub_f32_e32 v1, v1, v156
	v_sub_f32_e32 v0, v0, v156
	v_pk_mul_f32 v[0:1], v[0:1], v[158:159] op_sel_hi:[1,0]
	v_pk_mul_f32 v[2:3], v[2:3], v[158:159] op_sel_hi:[1,0]
	v_pk_fma_f32 v[0:1], v[236:237], v[0:1], v[252:253]
	v_pk_fma_f32 v[2:3], v[238:239], v[2:3], v[254:255]
	v_mov_b32_e32 v134, v8
	v_mov_b32_e32 v135, v9
	v_mov_b32_e32 v136, v10
	v_mov_b32_e32 v137, v11
	v_mov_b32_dpp v8, v0 row_ror:8 row_mask:0xf bank_mask:0xc
	v_mov_b32_dpp v9, v1 row_ror:8 row_mask:0xf bank_mask:0xc
	v_mov_b32_dpp v10, v2 row_ror:8 row_mask:0xf bank_mask:0xc
	v_mov_b32_dpp v11, v3 row_ror:8 row_mask:0xf bank_mask:0xc
	v_mov_b32_dpp v0, v134 row_ror:8 row_mask:0xf bank_mask:0x3
	v_mov_b32_dpp v1, v135 row_ror:8 row_mask:0xf bank_mask:0x3
	v_mov_b32_dpp v2, v136 row_ror:8 row_mask:0xf bank_mask:0x3
	v_mov_b32_dpp v3, v137 row_ror:8 row_mask:0xf bank_mask:0x3
	global_store_dwordx4 v[168:169], v[8:11], off offset:512
	global_store_dwordx4 v[170:171], v[0:3], off offset:512
	s_cmp_eq_u32 s40, 4
	s_cbranch_scc1 .LBB0_940
